# attention: first three K-fragment LDS reads of QK(t+1) issued before the tile barrier (tile waits vmcnt(2) so K(t+1) is already visible)
# speedup vs baseline: 1.0114x; 1.0064x over previous
.Ltb_u1_b:
	s_ashr_i32 s11, s6, 6
	s_lshl_b32 s10, s43, 4
	s_lshl_b32 s26, s11, 2
	v_bfe_u32 v233, v237, 4, 2
	s_and_b32 s60, s10, 0xfffff000
	v_or_b32_e32 v52, s26, v233
	s_waitcnt vmcnt(0)
	v_add_u32_e32 v2, s60, v52
	v_ashrrev_i32_e32 v3, 31, v2
	v_readlane_b32 s18, v252, 31
	v_bitop3_b32 v0, s26, v237, v233 bitop3:0x36
	v_lshlrev_b64 v[2:3], 12, v[2:3]
	v_readlane_b32 s19, v252, 32
	s_and_b32 s46, s43, 15
	s_lshl_b32 s84, s28, 8
	v_lshl_add_u64 v[2:3], s[18:19], 0, v[2:3]
	v_lshlrev_b32_e32 v0, 4, v0
	s_xor_b32 s17, s46, 31
	s_and_b32 s2, s11, 3
	v_lshl_add_u64 v[2:3], v[2:3], 0, s[84:85]
	v_and_b32_e32 v0, 0xf0, v0
	s_lshl_b32 s27, s11, 3
	v_bfe_u32 v53, v237, 3, 3
	s_lshl_b32 s21, s17, 7
	s_lshl_b32 s22, s2, 5
	s_lshl_b32 s18, s28, 7
	v_lshl_add_u64 v[2:3], v[2:3], 0, v[0:1]
	v_or_b32_e32 v0, s27, v53
	s_or_b32 s20, s22, s21
	v_lshrrev_b32_e32 v54, 1, v0
	v_add_u32_e32 v4, s18, v0
	v_and_b32_e32 v235, 31, v237
	v_xor_b32_e32 v6, v54, v237
	v_ashrrev_i32_e32 v5, 31, v4
	v_readlane_b32 s36, v252, 39
	s_or_b32 s10, s20, s60
	v_lshlrev_b64 v[4:5], 15, v[4:5]
	v_readlane_b32 s37, v252, 40
	v_lshlrev_b32_e32 v0, 4, v6
	v_or_b32_e32 v6, s10, v235
	v_lshl_add_u64 v[4:5], s[36:37], 0, v[4:5]
	v_ashrrev_i32_e32 v7, 31, v6
	v_readlane_b32 s36, v252, 17
	s_ashr_i32 s3, s6, 8
	v_lshlrev_b64 v[6:7], 12, v[6:7]
	v_readlane_b32 s37, v252, 18
	s_ashr_i32 s61, s60, 31
	v_bfe_u32 v234, v237, 5, 1
	v_lshl_add_u64 v[6:7], s[36:37], 0, v[6:7]
	s_lshl_b32 s36, s3, 6
	v_lshl_add_u64 v[4:5], s[60:61], 1, v[4:5]
	v_and_b32_e32 v0, 0x70, v0
	v_lshl_add_u64 v[6:7], v[6:7], 0, s[84:85]
	s_ashr_i32 s37, s36, 31
	v_lshl_add_u64 v[4:5], v[4:5], 0, v[0:1]
	v_lshl_add_u64 v[6:7], s[36:37], 1, v[6:7]
	v_lshlrev_b32_e32 v0, 4, v234
	v_lshl_add_u64 v[6:7], v[6:7], 0, v[0:1]
	global_load_dwordx4 v[146:149], v[6:7], off nt
	global_load_dwordx4 v[150:153], v[6:7], off offset:32 nt
	global_load_dwordx4 v[154:157], v[6:7], off offset:64 nt
	global_load_dwordx4 v[158:161], v[6:7], off offset:96 nt
	s_lshl_b32 s11, s11, 10
	s_add_i32 s11, s11, 0
	s_mov_b32 m0, s11
	s_mov_b64 s[36:37], 0x20000
	global_load_lds_dwordx4 v[2:3], off
	v_lshl_add_u64 v[8:9], v[2:3], 0, s[36:37]
	s_add_i32 m0, s11, 0x2000
	s_mov_b64 s[36:37], 0x40000
	global_load_lds_dwordx4 v[8:9], off
	s_add_i32 m0, s11, 0x4000
	v_lshl_add_u64 v[8:9], v[2:3], 0, s[36:37]
	s_mov_b64 s[36:37], 0x60000
	global_load_lds_dwordx4 v[8:9], off
	v_lshl_add_u64 v[8:9], v[2:3], 0, s[36:37]
	s_add_i32 m0, s11, 0x6000
	s_mov_b64 s[36:37], 0x200000
	global_load_lds_dwordx4 v[8:9], off
	s_add_i32 m0, s11, 0xc000
	v_lshl_add_u64 v[8:9], v[4:5], 0, s[36:37]
	global_load_lds_dwordx4 v[4:5], off
	s_add_i32 m0, s11, 0xe000
	s_mov_b64 s[36:37], 0xa0000
	global_load_lds_dwordx4 v[8:9], off
	s_add_i32 m0, s11, 0x8000
	v_lshl_add_u64 v[8:9], v[2:3], 0, s[34:35]
	global_load_lds_dwordx4 v[8:9], off
	v_lshl_add_u64 v[2:3], v[2:3], 0, s[36:37]
	s_add_i32 m0, s11, 0xa000
	s_mov_b64 s[36:37], 0x80
	global_load_lds_dwordx4 v[2:3], off
	s_add_i32 m0, s11, 0x10000
	v_lshl_add_u64 v[2:3], v[4:5], 0, s[36:37]
	s_mov_b64 s[36:37], 0x200080
	global_load_lds_dwordx4 v[2:3], off
	v_lshl_add_u64 v[2:3], v[4:5], 0, s[36:37]
	s_add_i32 m0, s11, 0x12000
	v_and_b32_e32 v0, 19, v237
	global_load_lds_dwordx4 v[2:3], off
	v_lshlrev_b32_e32 v2, 1, v237
	v_lshrrev_b32_e32 v35, 1, v34
	v_and_or_b32 v0, v2, 8, v0
	v_and_b32_e32 v22, 4, v35
	v_or_b32_e32 v2, v0, v22
	v_lshl_or_b32 v45, s3, 3, v234
	v_lshlrev_b32_e32 v44, 8, v2
	v_bitop3_b32 v2, v2, v45, 15 bitop3:0x6c
	v_lshl_add_u32 v239, v2, 4, v44
	s_waitcnt vmcnt(4)
	s_barrier
	v_add_u32_e32 v6, 0, v239
	v_bitop3_b32 v0, v0, 15, v22 bitop3:0xc8
	ds_read_b128 v[2:5], v6
	ds_read_b128 v[18:21], v6 offset:8192
	v_bitop3_b32 v22, v45, v0, 2 bitop3:0x36
	v_lshl_add_u32 v240, v22, 4, v44
	v_add_u32_e32 v40, 0, v240
	ds_read_b128 v[36:39], v40
	s_waitcnt vmcnt(0) lgkmcnt(0)
	v_mfma_f32_32x32x16_bf16 v[2:17], v[2:5], v[146:149], 0
	ds_read_b128 v[40:43], v40 offset:8192
	v_bfe_u32 v34, v34, 1, 3
	v_bitop3_b32 v57, v234, v34, 2 bitop3:0x36
	v_bitop3_b32 v58, v234, v34, 4 bitop3:0x36
	v_bitop3_b32 v59, v234, v34, 6 bitop3:0x36
	s_and_b32 s56, s42, 0xfffff000
	s_add_i32 s26, s26, s56
	v_mfma_f32_32x32x16_bf16 v[18:33], v[18:21], v[146:149], 0
	s_lshr_b32 s16, s43, 4
	s_and_b32 s16, s16, 15
	s_lshl_b32 s36, s16, 7
	s_lshl_b32 s37, s16, 8
	s_add_i32 s27, s27, s36
	s_ashr_i32 s57, s56, 31
	s_lshl_b64 s[44:45], s[56:57], 1
	v_mfma_f32_32x32x16_bf16 v[2:17], v[36:39], v[150:153], v[2:17]
	v_bitop3_b32 v36, v45, v0, 4 bitop3:0x36
	v_lshl_add_u32 v241, v36, 4, v44
	v_add_u32_e32 v46, 0, v241
	ds_read_b128 v[36:39], v46
	v_bitop3_b32 v0, v45, v0, 6 bitop3:0x36
	v_lshl_add_u32 v243, v0, 4, v44
	v_add_u32_e32 v0, 0, v243
	s_waitcnt lgkmcnt(1)
	v_mfma_f32_32x32x16_bf16 v[18:33], v[40:43], v[150:153], v[18:33]
	ds_read_b128 v[40:43], v46 offset:8192
	v_lshlrev_b32_e32 v236, 3, v234
	s_mov_b32 s84, s85
	v_bitop3_b32 v56, v35, v234, 7 bitop3:0x6c
	s_mov_b32 s86, s85
	s_mov_b32 s87, s85
	s_mov_b32 s88, s85
	s_waitcnt lgkmcnt(1)
	v_mfma_f32_32x32x16_bf16 v[2:17], v[36:39], v[154:157], v[2:17]
	ds_read_b128 v[36:39], v0
	s_mov_b32 s89, s85
	s_mov_b32 s90, s85
	s_mov_b32 s91, s85
	s_mov_b32 s92, s85
	s_mov_b32 s93, s85
	s_mov_b32 s94, s85
	s_waitcnt lgkmcnt(1)
	v_mfma_f32_32x32x16_bf16 v[18:33], v[40:43], v[154:157], v[18:33]
	ds_read_b128 v[40:43], v0 offset:8192
	s_mov_b32 s95, s85
	s_mov_b32 s96, s85
	s_mov_b32 s97, s85
	s_mov_b32 s98, s85
	s_mov_b32 s99, s85
	s_lshl_b32 s16, s17, 1
	s_waitcnt lgkmcnt(1)
	v_mfma_f32_32x32x16_bf16 v[2:17], v[36:39], v[158:161], v[2:17]
	v_lshlrev_b32_e32 v55, 7, v235
	s_lshr_b32 s19, s20, 6
	s_add_i32 s17, s16, 2
	s_add_i32 s19, s19, 1
	v_lshl_or_b32 v244, v56, 4, v55
	v_lshl_or_b32 v245, v57, 4, v55
	v_lshl_or_b32 v246, v58, 4, v55
	s_waitcnt lgkmcnt(0)
	v_mfma_f32_32x32x16_bf16 v[18:33], v[40:43], v[158:161], v[18:33]
	s_nop 2
	v_max_f32_e32 v34, v3, v3
	v_lshl_or_b32 v247, v59, 4, v55
	s_mov_b32 s23, 1
	v_and_b32_e32 v238, 63, v237
	s_mov_b32 s31, 2
	s_min_u32 s19, s17, s19
	s_addk_i32 s20, 0xff50
	s_nop 1
	v_max_f32_e32 v0, v19, v19
	v_max_f32_e32 v0, v34, v0
	v_max3_f32 v0, v2, v18, v0
	v_max3_f32 v34, v20, v5, v21
	v_max3_f32 v0, v0, v4, v34
	v_max3_f32 v34, v22, v7, v23
	v_max3_f32 v0, v0, v6, v34
	v_max3_f32 v34, v24, v9, v25
	v_max3_f32 v0, v0, v8, v34
	v_max3_f32 v34, v26, v11, v27
	v_max3_f32 v0, v0, v10, v34
	v_max3_f32 v34, v28, v13, v29
	v_max3_f32 v0, v0, v12, v34
	v_max3_f32 v34, v30, v15, v31
	v_max3_f32 v0, v0, v14, v34
	v_max3_f32 v34, v32, v17, v33
	v_max3_f32 v0, v0, v16, v34
	v_mov_b32_e32 v34, v0
	s_nop 1
	v_permlane32_swap_b32_e32 v0, v34
	v_max_f32_e32 v34, v34, v34
	v_max_f32_e32 v0, v0, v0
	v_max_f32_e32 v213, v0, v34
	v_sub_f32_e32 v0, v2, v213
	v_exp_f32_e32 v60, v0
	v_sub_f32_e32 v0, v18, v213
	v_exp_f32_e32 v61, v0
	v_sub_f32_e32 v0, v3, v213
	v_sub_f32_e32 v2, v19, v213
	v_exp_f32_e32 v0, v0
	v_exp_f32_e32 v2, v2
	v_add_f32_e32 v3, v61, v60
	v_mov_b64_e32 v[34:35], s[84:85]
	v_cvt_pk_bf16_f32 v162, v60, v0
	v_pk_add_f32 v[18:19], v[2:3], v[0:1]
	v_sub_f32_e32 v3, v4, v213
	v_sub_f32_e32 v4, v20, v213
	v_pk_add_f32 v[18:19], v[18:19], v[18:19] op_sel_hi:[0,1]
	v_exp_f32_e32 v62, v4
	v_sub_f32_e32 v4, v5, v213
	v_exp_f32_e32 v3, v3
	v_exp_f32_e32 v18, v4
	v_sub_f32_e32 v4, v21, v213
	v_exp_f32_e32 v4, v4
	v_add_f32_e32 v5, v62, v3
	v_sub_u32_e32 v0, 7, v237
	v_cvt_pk_bf16_f32 v178, v61, v2
	v_pk_add_f32 v[20:21], v[4:5], v[18:19]
	v_sub_f32_e32 v5, v6, v213
	v_sub_f32_e32 v6, v22, v213
	v_pk_add_f32 v[20:21], v[20:21], v[20:21] op_sel_hi:[0,1]
	v_exp_f32_e32 v19, v6
	v_sub_f32_e32 v6, v7, v213
	v_exp_f32_e32 v5, v5
	v_exp_f32_e32 v20, v6
	v_sub_f32_e32 v6, v23, v213
	v_exp_f32_e32 v6, v6
	v_add_f32_e32 v7, v19, v5
	v_and_b32_e32 v0, 3, v0
	v_mov_b32_e32 v2, s33
	v_pk_add_f32 v[22:23], v[6:7], v[20:21]
	v_sub_f32_e32 v7, v8, v213
	v_sub_f32_e32 v8, v24, v213
	v_pk_add_f32 v[22:23], v[22:23], v[22:23] op_sel_hi:[0,1]
	v_exp_f32_e32 v21, v8
	v_sub_f32_e32 v8, v9, v213
	v_exp_f32_e32 v7, v7
	v_exp_f32_e32 v22, v8
	v_sub_f32_e32 v8, v25, v213
	v_exp_f32_e32 v8, v8
	v_add_f32_e32 v9, v21, v7
	s_movk_i32 s33, 0x510
	v_mad_u32_u24 v0, v0, s33, v2
	v_pk_add_f32 v[24:25], v[8:9], v[22:23]
	v_sub_f32_e32 v9, v10, v213
	v_sub_f32_e32 v10, v26, v213
	v_pk_add_f32 v[24:25], v[24:25], v[24:25] op_sel_hi:[0,1]
	v_exp_f32_e32 v23, v10
	v_sub_f32_e32 v10, v11, v213
	v_exp_f32_e32 v9, v9
	v_exp_f32_e32 v24, v10
	v_sub_f32_e32 v10, v27, v213
	v_exp_f32_e32 v10, v10
	v_add_f32_e32 v11, v23, v9
	v_or_b32_e32 v2, s26, v233
	v_cvt_pk_bf16_f32 v163, v3, v18
	v_pk_add_f32 v[26:27], v[10:11], v[24:25]
	v_sub_f32_e32 v11, v12, v213
	v_sub_f32_e32 v12, v28, v213
	v_pk_add_f32 v[26:27], v[26:27], v[26:27] op_sel_hi:[0,1]
	v_exp_f32_e32 v25, v12
	v_sub_f32_e32 v12, v13, v213
	v_exp_f32_e32 v11, v11
	v_exp_f32_e32 v26, v12
	v_sub_f32_e32 v12, v29, v213
	v_exp_f32_e32 v12, v12
	v_add_f32_e32 v13, v25, v11
	v_ashrrev_i32_e32 v3, 31, v2
	v_lshlrev_b64 v[214:215], 12, v[2:3]
	v_pk_add_f32 v[28:29], v[12:13], v[26:27]
	v_sub_f32_e32 v13, v14, v213
	v_sub_f32_e32 v14, v30, v213
	v_pk_add_f32 v[28:29], v[28:29], v[28:29] op_sel_hi:[0,1]
	v_exp_f32_e32 v27, v14
	v_sub_f32_e32 v14, v15, v213
	v_exp_f32_e32 v13, v13
	v_exp_f32_e32 v28, v14
	v_sub_f32_e32 v14, v31, v213
	v_exp_f32_e32 v14, v14
	v_sub_f32_e32 v15, v16, v213
	v_exp_f32_e32 v63, v15
	v_sub_f32_e32 v15, v32, v213
	v_exp_f32_e32 v32, v15
	v_add_f32_e32 v15, v27, v13
	v_pk_add_f32 v[30:31], v[14:15], v[28:29]
	v_bitop3_b32 v2, v52, 15, v237 bitop3:0x48
	v_pk_add_f32 v[30:31], v[30:31], v[30:31] op_sel_hi:[0,1]
	v_sub_f32_e32 v15, v17, v213
	v_lshlrev_b32_e32 v2, 4, v2
	v_exp_f32_e32 v30, v15
	v_sub_f32_e32 v15, v33, v213
	v_or3_b32 v214, v214, s37, v2
	v_or_b32_e32 v2, s27, v53
	v_exp_f32_e32 v50, v15
	v_ashrrev_i32_e32 v3, 31, v2
	v_cvt_pk_bf16_f32 v179, v62, v4
	v_lshlrev_b64 v[2:3], 15, v[2:3]
	v_bitop3_b32 v4, v54, 7, v237 bitop3:0x48
	v_lshl_or_b32 v2, v4, 4, v2
	v_add_f32_e32 v51, v32, v63
	v_lshl_add_u64 v[216:217], v[2:3], 0, s[44:45]
	v_sub_u32_e32 v2, v236, v235
	v_mov_b64_e32 v[48:49], s[98:99]
	v_pk_add_f32 v[16:17], v[50:51], v[30:31]
	v_subrev_u32_e32 v2, s22, v2
	v_mov_b64_e32 v[36:37], s[86:87]
	v_mov_b64_e32 v[38:39], s[88:89]
	v_mov_b64_e32 v[40:41], s[90:91]
	v_mov_b64_e32 v[42:43], s[92:93]
	v_mov_b64_e32 v[44:45], s[94:95]
	v_mov_b64_e32 v[46:47], s[96:97]
	v_xor_b32_e32 v66, 0x80000000, v213
	v_add_f32_e32 v242, v16, v17
	v_cvt_pk_bf16_f32 v164, v5, v20
	v_cvt_pk_bf16_f32 v165, v7, v22
	v_cvt_pk_bf16_f32 v170, v9, v24
	v_cvt_pk_bf16_f32 v171, v11, v26
	v_cvt_pk_bf16_f32 v172, v13, v28
	v_cvt_pk_bf16_f32 v173, v63, v30
	v_cvt_pk_bf16_f32 v180, v19, v6
	v_cvt_pk_bf16_f32 v181, v21, v8
	v_cvt_pk_bf16_f32 v186, v23, v10
	v_cvt_pk_bf16_f32 v187, v25, v12
	v_cvt_pk_bf16_f32 v188, v27, v14
	v_cvt_pk_bf16_f32 v189, v32, v50
	v_subrev_u32_e32 v248, s21, v2
	v_mov_b64_e32 v[64:65], v[48:49]
	v_mov_b64_e32 v[18:19], v[34:35]
	v_mov_b64_e32 v[2:3], v[34:35]
	v_readlane_b32 s94, v255, 10
	v_readlane_b32 s90, v255, 12
	v_mov_b32_e32 v67, v66
	v_mov_b32_e32 v68, v66
	v_mov_b32_e32 v69, v66
	v_mov_b32_e32 v70, v66
	v_mov_b32_e32 v71, v66
	v_mov_b32_e32 v72, v66
	v_mov_b32_e32 v73, v66
	v_mov_b32_e32 v74, v66
	v_mov_b32_e32 v75, v66
	v_mov_b32_e32 v76, v66
	v_mov_b32_e32 v77, v66
	v_mov_b32_e32 v78, v66
	v_mov_b32_e32 v79, v66
	v_mov_b32_e32 v80, v66
	v_mov_b32_e32 v81, v66
	s_mov_b32 s21, 0
	v_mov_b32_e32 v166, 0
	v_mov_b32_e32 v167, 0
	v_mov_b32_e32 v168, 0
	v_mov_b32_e32 v169, 0
	v_mov_b32_e32 v174, 0
	v_mov_b32_e32 v175, 0
	v_mov_b32_e32 v176, 0
	v_mov_b32_e32 v177, 0
	v_mov_b32_e32 v182, 0
	v_mov_b32_e32 v183, 0
	v_mov_b32_e32 v184, 0
	v_mov_b32_e32 v185, 0
	v_mov_b32_e32 v190, 0
	v_mov_b32_e32 v191, 0
	v_mov_b32_e32 v192, 0
	v_mov_b32_e32 v193, 0
	v_mov_b64_e32 v[62:63], v[46:47]
	v_mov_b64_e32 v[60:61], v[44:45]
	v_mov_b64_e32 v[58:59], v[42:43]
	v_mov_b64_e32 v[56:57], v[40:41]
	v_mov_b64_e32 v[54:55], v[38:39]
	v_mov_b64_e32 v[52:53], v[36:37]
	v_mov_b64_e32 v[50:51], v[34:35]
	v_mov_b64_e32 v[20:21], v[36:37]
	v_mov_b64_e32 v[22:23], v[38:39]
	v_mov_b64_e32 v[24:25], v[40:41]
	v_mov_b64_e32 v[26:27], v[42:43]
	v_mov_b64_e32 v[28:29], v[44:45]
	v_mov_b64_e32 v[30:31], v[46:47]
	v_mov_b64_e32 v[32:33], v[48:49]
	v_mov_b64_e32 v[4:5], v[36:37]
	v_mov_b64_e32 v[6:7], v[38:39]
	v_mov_b64_e32 v[8:9], v[40:41]
	v_mov_b64_e32 v[10:11], v[42:43]
	v_mov_b64_e32 v[12:13], v[44:45]
	v_mov_b64_e32 v[14:15], v[46:47]
	v_mov_b64_e32 v[16:17], v[48:49]
	s_mov_b32 s33, 1
	s_mov_b32 s48, 0
	s_mov_b32 s49, 0
	s_movk_i32 s92, 0x6e
	s_movk_i32 s93, 0xd0
	s_mov_b32 s57, 0x41000000
	v_readlane_b32 s95, v255, 11
	v_readlane_b32 s91, v255, 13
	s_mov_b64 s[62:63], 0xd0e0000
	s_mov_b64 s[96:97], 0x15000100
.LBB0_164:
	s_add_i32 s22, s23, -1
	s_cmp_lt_u32 s22, s16
	s_cselect_b64 s[88:89], -1, 0
	s_cmp_ge_u32 s22, s16
	s_cselect_b64 s[86:87], -1, 0
	s_mov_b64 s[26:27], -1
	s_and_b64 vcc, exec, s[86:87]
	s_cbranch_vccz .LBB0_166
	s_waitcnt vmcnt(2)
	s_mov_b64 s[26:27], 0
.LBB0_166:
	s_andn2_b64 vcc, exec, s[26:27]
	s_cbranch_vccnz .LBB0_168
	s_waitcnt vmcnt(2)
.LBB0_168:
	s_lshl_b32 s101, s33, 14
	s_nop 1
	v_add_u32_e32 v82, s101, v239
	v_add_u32_e32 v102, s101, v240
	ds_read_b128 v[98:101], v82
	ds_read_b128 v[114:117], v82 offset:8192
	ds_read_b128 v[118:121], v102
	s_barrier
	s_cmp_lt_u32 s22, s19
	s_mov_b64 s[26:27], -1
	s_cbranch_scc1 .LBB0_174
	s_add_i32 s22, s23, 2
	s_cmp_ge_u32 s22, s17
	s_cbranch_scc1 .LBB0_171
	s_lshl_b32 s26, s48, 14
	s_add_i32 s26, s11, s26
	s_add_i32 s27, s26, 0x2000
	s_mov_b32 m0, s26
	s_add_u32 s100, s8, s80
	s_addc_u32 s101, s9, s81
	global_load_lds_dwordx4 v214, s[100:101]
	s_mov_b32 m0, s27
	s_add_u32 s100, s8, s62
	s_addc_u32 s101, s9, s63
	global_load_lds_dwordx4 v214, s[100:101]

.LBB0_185:
	s_and_b64 vcc, exec, s[26:27]
	s_cbranch_vccz .LBB0_199
	s_lshl_b32 s22, s33, 14
	s_add_i32 s22, s22, 0
	s_nop 1
	s_waitcnt lgkmcnt(0)
	v_mfma_f32_32x32x16_bf16 v[82:97], v[98:101], v[146:149], v[66:81]
	ds_read_b128 v[122:125], v102 offset:8192
	v_mfma_f32_32x32x16_bf16 v[98:113], v[114:117], v[146:149], v[66:81]
	v_add_u32_e32 v126, s22, v241
	ds_read_b128 v[114:117], v126
	v_mfma_f32_32x32x16_bf16 v[82:97], v[118:121], v[150:153], v[82:97]
	ds_read_b128 v[118:121], v126 offset:8192
	s_waitcnt lgkmcnt(0)
	v_mfma_f32_32x32x16_bf16 v[98:113], v[122:125], v[150:153], v[98:113]
	v_add_u32_e32 v126, s22, v243
	ds_read_b128 v[122:125], v126
	v_mfma_f32_32x32x16_bf16 v[82:97], v[114:117], v[154:157], v[82:97]
	ds_read_b128 v[114:117], v126 offset:8192
	v_mfma_f32_32x32x16_bf16 v[98:113], v[118:121], v[154:157], v[98:113]
	s_waitcnt lgkmcnt(0)
	v_mfma_f32_32x32x16_bf16 v[82:97], v[122:125], v[158:161], v[82:97]
	v_mfma_f32_32x32x16_bf16 v[98:113], v[114:117], v[158:161], v[98:113]
	ds_read_b128 v[126:129], v249 offset:49152
	ds_read_b128 v[122:125], v249 offset:53248
	ds_read_b128 v[118:121], v249 offset:57344
	ds_read_b128 v[114:117], v249 offset:61440
	s_add_i32 s22, s21, 64
	s_cmp_le_u32 s22, s20
	s_cbranch_scc1 .LBB0_188
	v_add_u32_e32 v130, s21, v248
	v_add_u32_e32 v130, 0x11f, v130
	v_and_b32_e32 v130, 0x3ffffffc, v130
	v_lshl_add_u32 v166, v130, 2, v0
	ds_read_b128 v[130:133], v166
	ds_read_b128 v[134:137], v166 offset:16
	ds_read_b128 v[138:141], v166 offset:64
	ds_read_b128 v[142:145], v166 offset:80
	s_waitcnt lgkmcnt(0)
	v_pk_add_f32 v[84:85], v[84:85], v[132:133]
	v_pk_add_f32 v[86:87], v[86:87], v[134:135]
	v_pk_add_f32 v[90:91], v[90:91], v[138:139]
	v_pk_add_f32 v[94:95], v[94:95], v[142:143]
	v_pk_add_f32 v[96:97], v[96:97], v[144:145]
	v_pk_add_f32 v[92:93], v[92:93], v[140:141]
	v_pk_add_f32 v[88:89], v[88:89], v[136:137]
	v_pk_add_f32 v[82:83], v[82:83], v[130:131]
	ds_read_b128 v[130:133], v166 offset:128
	ds_read_b128 v[134:137], v166 offset:144
	ds_read_b128 v[138:141], v166 offset:192
	ds_read_b128 v[142:145], v166 offset:208
	s_waitcnt lgkmcnt(0)
	v_pk_add_f32 v[100:101], v[100:101], v[132:133]
	v_pk_add_f32 v[102:103], v[102:103], v[134:135]
	v_pk_add_f32 v[106:107], v[106:107], v[138:139]
	v_pk_add_f32 v[110:111], v[110:111], v[142:143]
	v_pk_add_f32 v[112:113], v[112:113], v[144:145]
	v_pk_add_f32 v[108:109], v[108:109], v[140:141]
	v_pk_add_f32 v[104:105], v[104:105], v[136:137]
	v_pk_add_f32 v[98:99], v[98:99], v[130:131]

.LBB0_205:
	s_mov_b64 s[26:27], 0
.LBB0_206:
	s_andn2_b64 vcc, exec, s[26:27]
	s_cbranch_vccnz .LBB0_208
	s_waitcnt vmcnt(2)
.LBB0_208:
	s_add_i32 s26, s33, 1
	s_cmp_lg_u32 s33, 2
	s_cselect_b32 s33, s26, 0
	s_add_i32 s26, s48, 1
	s_cmp_lg_u32 s48, 2
	s_cselect_b32 s48, s26, 0
	s_add_i32 s26, s49, 1
	s_cmp_lg_u32 s49, 2
	s_cselect_b32 s49, s26, 0
	s_add_i32 s26, s31, 1
	s_lshl_b32 s101, s33, 14
	s_nop 1
	v_add_u32_e32 v82, s101, v239
	v_add_u32_e32 v102, s101, v240
	ds_read_b128 v[98:101], v82
	ds_read_b128 v[114:117], v82 offset:8192
	ds_read_b128 v[118:121], v102
	s_barrier
	s_cmp_lg_u32 s31, 2
	s_cselect_b32 s31, s26, 0
	s_cmp_lt_u32 s23, s19
	s_mov_b64 s[26:27], -1
	s_cbranch_scc1 .LBB0_214
	s_add_i32 s26, s23, 3
	s_cmp_gt_u32 s26, s16
	s_cbranch_scc1 .LBB0_211
	s_lshl_b32 s26, s48, 14
	s_add_i32 s26, s11, s26
	s_add_i32 s27, s26, 0x2000
	s_mov_b32 m0, s26
	s_add_u32 s100, s8, s50
	s_addc_u32 s101, s9, s51
	global_load_lds_dwordx4 v214, s[100:101]
	s_mov_b32 m0, s27
	s_add_u32 s100, s8, s4
	s_addc_u32 s101, s9, s5
	global_load_lds_dwordx4 v214, s[100:101]

.LBB0_225:
	s_and_b64 vcc, exec, s[26:27]
	s_cbranch_vccz .LBB0_239
	s_lshl_b32 s26, s33, 14
	s_add_i32 s26, s26, 0
	s_nop 1
	s_waitcnt lgkmcnt(0)
	v_mfma_f32_32x32x16_bf16 v[82:97], v[98:101], v[146:149], v[66:81]
	ds_read_b128 v[122:125], v102 offset:8192
	v_mfma_f32_32x32x16_bf16 v[98:113], v[114:117], v[146:149], v[66:81]
	v_add_u32_e32 v126, s26, v241
	ds_read_b128 v[114:117], v126
	v_mfma_f32_32x32x16_bf16 v[82:97], v[118:121], v[150:153], v[82:97]
	ds_read_b128 v[118:121], v126 offset:8192
	s_waitcnt lgkmcnt(0)
	v_mfma_f32_32x32x16_bf16 v[98:113], v[122:125], v[150:153], v[98:113]
	v_add_u32_e32 v126, s26, v243
	ds_read_b128 v[122:125], v126
	v_mfma_f32_32x32x16_bf16 v[82:97], v[114:117], v[154:157], v[82:97]
	ds_read_b128 v[114:117], v126 offset:8192
	v_mfma_f32_32x32x16_bf16 v[98:113], v[118:121], v[154:157], v[98:113]
	s_waitcnt lgkmcnt(0)
	v_mfma_f32_32x32x16_bf16 v[82:97], v[122:125], v[158:161], v[82:97]
	v_mfma_f32_32x32x16_bf16 v[98:113], v[114:117], v[158:161], v[98:113]
	ds_read_b128 v[126:129], v249 offset:49152
	ds_read_b128 v[122:125], v249 offset:53248
	ds_read_b128 v[118:121], v249 offset:57344
	ds_read_b128 v[114:117], v249 offset:61440
	s_add_i32 s26, s21, 0x80
	s_cmp_le_u32 s26, s20
	s_cbranch_scc1 .LBB0_228
	v_add_u32_e32 v130, s21, v248
	v_add_u32_e32 v130, 0x15f, v130
	v_and_b32_e32 v130, 0x3ffffffc, v130
	v_lshl_add_u32 v162, v130, 2, v0
	ds_read_b128 v[130:133], v162
	ds_read_b128 v[134:137], v162 offset:16
	ds_read_b128 v[138:141], v162 offset:64
	ds_read_b128 v[142:145], v162 offset:80
	s_waitcnt lgkmcnt(0)
	v_pk_add_f32 v[84:85], v[84:85], v[132:133]
	v_pk_add_f32 v[86:87], v[86:87], v[134:135]
	v_pk_add_f32 v[90:91], v[90:91], v[138:139]
	v_pk_add_f32 v[94:95], v[94:95], v[142:143]
	v_pk_add_f32 v[96:97], v[96:97], v[144:145]
	v_pk_add_f32 v[92:93], v[92:93], v[140:141]
	v_pk_add_f32 v[88:89], v[88:89], v[136:137]
	v_pk_add_f32 v[82:83], v[82:83], v[130:131]
	ds_read_b128 v[130:133], v162 offset:128
	ds_read_b128 v[134:137], v162 offset:144
	ds_read_b128 v[138:141], v162 offset:192
	ds_read_b128 v[142:145], v162 offset:208
	s_waitcnt lgkmcnt(0)
	v_pk_add_f32 v[100:101], v[100:101], v[132:133]
	v_pk_add_f32 v[102:103], v[102:103], v[134:135]
	v_pk_add_f32 v[106:107], v[106:107], v[138:139]
	v_pk_add_f32 v[110:111], v[110:111], v[142:143]
	v_pk_add_f32 v[112:113], v[112:113], v[144:145]
	v_pk_add_f32 v[108:109], v[108:109], v[140:141]
	v_pk_add_f32 v[104:105], v[104:105], v[136:137]
	v_pk_add_f32 v[98:99], v[98:99], v[130:131]

.LBB0_261:
	s_and_b32 s2, s2, 3
	s_lshl_b32 s11, s46, 7
	s_lshl_b32 s28, s2, 5
	s_or_b32 s16, s28, s11
	v_and_b32_e32 v235, 31, v237
	s_or_b32 s11, s16, s60
	v_or_b32_e32 v6, s11, v235
	v_ashrrev_i32_e32 v7, 31, v6
	v_readlane_b32 s18, v252, 17
	s_ashr_i32 s6, s3, 8
	v_lshlrev_b64 v[6:7], 12, v[6:7]
	v_readlane_b32 s19, v252, 18
	v_and_b32_e32 v238, 63, v237
	v_lshrrev_b32_e32 v234, 5, v238
	v_lshl_add_u64 v[6:7], s[18:19], 0, v[6:7]
	s_lshl_b32 s18, s6, 6
	v_lshl_add_u64 v[6:7], v[6:7], 0, s[84:85]
	s_ashr_i32 s19, s18, 31
	v_lshl_add_u64 v[6:7], s[18:19], 1, v[6:7]
	v_lshlrev_b32_e32 v0, 4, v234
	v_lshl_add_u64 v[6:7], v[6:7], 0, v[0:1]
	global_load_dwordx4 v[146:149], v[6:7], off nt
	global_load_dwordx4 v[150:153], v[6:7], off offset:32 nt
	global_load_dwordx4 v[154:157], v[6:7], off offset:64 nt
	global_load_dwordx4 v[158:161], v[6:7], off offset:96 nt
	s_mov_b64 s[18:19], 0x80
	s_add_i32 m0, s10, 0x10000
	v_lshl_add_u64 v[8:9], v[4:5], 0, s[18:19]
	s_mov_b64 s[18:19], 0x200080
	v_lshl_add_u64 v[4:5], v[4:5], 0, s[18:19]
	global_load_lds_dwordx4 v[8:9], off
	s_add_i32 m0, s10, 0x12000
	v_and_b32_e32 v0, 19, v237
	global_load_lds_dwordx4 v[4:5], off
	v_lshlrev_b32_e32 v3, 1, v237
	v_lshrrev_b32_e32 v38, 1, v2
	v_and_or_b32 v0, v3, 8, v0
	v_and_b32_e32 v22, 4, v38
	v_or_b32_e32 v2, v0, v22
	v_lshl_or_b32 v37, s6, 3, v234
	v_lshlrev_b32_e32 v39, 8, v2
	v_bitop3_b32 v2, v2, v37, 15 bitop3:0x6c
	v_lshl_add_u32 v239, v2, 4, v39
	v_add_u32_e32 v18, 0, v239
	s_waitcnt vmcnt(4)
	s_barrier
	ds_read_b128 v[2:5], v18
	v_bitop3_b32 v0, v0, 15, v22 bitop3:0xc8
	v_bitop3_b32 v22, v37, v0, 2 bitop3:0x36
	v_lshl_add_u32 v240, v22, 4, v39
	v_add_u32_e32 v44, 0, v240
	ds_read_b128 v[40:43], v44
	ds_read_b128 v[18:21], v18 offset:8192
	s_mov_b64 s[26:27], -1
	s_cmpk_lt_u32 s16, 0xb0
	s_waitcnt vmcnt(0) lgkmcnt(0)
	v_mfma_f32_32x32x16_bf16 v[2:17], v[2:5], v[146:149], 0
	v_mfma_f32_32x32x16_bf16 v[2:17], v[40:43], v[150:153], v[2:17]
	ds_read_b128 v[40:43], v44 offset:8192
	v_bitop3_b32 v44, v37, v0, 4 bitop3:0x36
	v_lshl_add_u32 v241, v44, 4, v39
	v_add_u32_e32 v44, 0, v241
	v_bitop3_b32 v0, v37, v0, 6 bitop3:0x36
	v_lshl_add_u32 v242, v0, 4, v39
	v_add_u32_e32 v0, 0, v242
	v_mfma_f32_32x32x16_bf16 v[18:33], v[18:21], v[146:149], 0
	v_or_b32_e32 v37, s16, v235
	s_waitcnt lgkmcnt(0)
	v_mfma_f32_32x32x16_bf16 v[18:33], v[40:43], v[150:153], v[18:33]
	ds_read_b128 v[40:43], v44
	s_waitcnt lgkmcnt(0)
	v_mfma_f32_32x32x16_bf16 v[2:17], v[40:43], v[154:157], v[2:17]
	ds_read_b128 v[40:43], v44 offset:8192
	s_waitcnt lgkmcnt(0)
	v_mfma_f32_32x32x16_bf16 v[18:33], v[40:43], v[154:157], v[18:33]
	ds_read_b128 v[40:43], v0
	s_waitcnt lgkmcnt(0)
	v_mfma_f32_32x32x16_bf16 v[2:17], v[40:43], v[158:161], v[2:17]
	ds_read_b128 v[40:43], v0 offset:8192
	s_waitcnt lgkmcnt(0)
	v_mfma_f32_32x32x16_bf16 v[18:33], v[40:43], v[158:161], v[18:33]
	s_cbranch_scc1 .LBB0_263
	v_or_b32_e32 v0, s16, v235
	s_mov_b64 s[26:27], 0

.LBB0_267:
	s_add_i32 s21, s22, -1
	s_cmp_lt_u32 s21, s17
	s_cselect_b64 s[44:45], -1, 0
	s_cmp_ge_u32 s21, s17
	s_cselect_b64 s[38:39], -1, 0
	s_mov_b64 s[26:27], -1
	s_and_b64 vcc, exec, s[38:39]
	s_cbranch_vccz .LBB0_269
	s_waitcnt vmcnt(2)
	s_mov_b64 s[26:27], 0
.LBB0_269:
	s_andn2_b64 vcc, exec, s[26:27]
	s_cbranch_vccnz .LBB0_271
	s_waitcnt vmcnt(2)
.LBB0_271:
	s_lshl_b32 s101, s31, 14
	s_nop 1
	v_add_u32_e32 v82, s101, v239
	v_add_u32_e32 v102, s101, v240
	ds_read_b128 v[98:101], v82
	ds_read_b128 v[114:117], v82 offset:8192
	ds_read_b128 v[118:121], v102
	s_barrier
	s_cmp_lt_u32 s21, s19
	s_mov_b64 s[26:27], -1
	s_cbranch_scc1 .LBB0_277
	s_add_i32 s21, s22, 2
	s_cmp_ge_u32 s21, s18
	s_cbranch_scc1 .LBB0_274
	s_lshl_b32 s26, s28, 14
	s_add_i32 s26, s10, s26
	s_add_i32 s27, s26, 0x2000
	s_mov_b32 m0, s26
	s_add_u32 s100, s8, s80
	s_addc_u32 s101, s9, s81
	global_load_lds_dwordx4 v214, s[100:101]
	s_mov_b32 m0, s27
	s_add_u32 s100, s8, s62
	s_addc_u32 s101, s9, s63
	global_load_lds_dwordx4 v214, s[100:101]

.LBB0_288:
	s_and_b64 vcc, exec, s[26:27]
	s_cbranch_vccz .LBB0_302
	s_lshl_b32 s21, s31, 14
	s_add_i32 s21, s21, 0
	s_nop 1
	s_waitcnt lgkmcnt(0)
	v_mfma_f32_32x32x16_bf16 v[82:97], v[98:101], v[146:149], v[66:81]
	ds_read_b128 v[122:125], v102 offset:8192
	v_mfma_f32_32x32x16_bf16 v[98:113], v[114:117], v[146:149], v[66:81]
	v_add_u32_e32 v126, s21, v241
	ds_read_b128 v[114:117], v126
	v_mfma_f32_32x32x16_bf16 v[82:97], v[118:121], v[150:153], v[82:97]
	ds_read_b128 v[118:121], v126 offset:8192
	s_waitcnt lgkmcnt(0)
	v_mfma_f32_32x32x16_bf16 v[98:113], v[122:125], v[150:153], v[98:113]
	v_add_u32_e32 v126, s21, v242
	ds_read_b128 v[122:125], v126
	v_mfma_f32_32x32x16_bf16 v[82:97], v[114:117], v[154:157], v[82:97]
	ds_read_b128 v[114:117], v126 offset:8192
	v_mfma_f32_32x32x16_bf16 v[98:113], v[118:121], v[154:157], v[98:113]
	s_waitcnt lgkmcnt(0)
	v_mfma_f32_32x32x16_bf16 v[82:97], v[122:125], v[158:161], v[82:97]
	v_mfma_f32_32x32x16_bf16 v[98:113], v[114:117], v[158:161], v[98:113]
	ds_read_b128 v[126:129], v212 offset:49152
	ds_read_b128 v[122:125], v212 offset:53248
	ds_read_b128 v[118:121], v212 offset:57344
	ds_read_b128 v[114:117], v212 offset:61440
	s_cmp_le_u32 s20, s16
	s_cbranch_scc1 .LBB0_291
	v_add3_u32 v130, v249, s20, 47
	v_and_b32_e32 v130, 0x3ffffffc, v130
	v_lshl_add_u32 v166, v130, 2, v244
	ds_read_b128 v[130:133], v166
	ds_read_b128 v[134:137], v166 offset:16
	ds_read_b128 v[138:141], v166 offset:64
	ds_read_b128 v[142:145], v166 offset:80
	s_waitcnt lgkmcnt(0)
	v_pk_add_f32 v[84:85], v[84:85], v[132:133]
	v_pk_add_f32 v[88:89], v[88:89], v[136:137]
	v_pk_add_f32 v[92:93], v[92:93], v[140:141]
	v_pk_add_f32 v[96:97], v[96:97], v[144:145]
	v_pk_add_f32 v[94:95], v[94:95], v[142:143]
	v_pk_add_f32 v[90:91], v[90:91], v[138:139]
	v_pk_add_f32 v[86:87], v[86:87], v[134:135]
	v_pk_add_f32 v[82:83], v[82:83], v[130:131]
	ds_read_b128 v[130:133], v166 offset:128
	ds_read_b128 v[134:137], v166 offset:144
	ds_read_b128 v[138:141], v166 offset:192
	ds_read_b128 v[142:145], v166 offset:208
	s_waitcnt lgkmcnt(0)
	v_pk_add_f32 v[100:101], v[100:101], v[132:133]
	v_pk_add_f32 v[104:105], v[104:105], v[136:137]
	v_pk_add_f32 v[108:109], v[108:109], v[140:141]
	v_pk_add_f32 v[112:113], v[112:113], v[144:145]
	v_pk_add_f32 v[110:111], v[110:111], v[142:143]
	v_pk_add_f32 v[106:107], v[106:107], v[138:139]
	v_pk_add_f32 v[102:103], v[102:103], v[134:135]
	v_pk_add_f32 v[98:99], v[98:99], v[130:131]

.LBB0_308:
	s_mov_b64 s[26:27], 0
.LBB0_309:
	s_andn2_b64 vcc, exec, s[26:27]
	s_cbranch_vccnz .LBB0_311
	s_waitcnt vmcnt(2)
.LBB0_311:
	s_add_i32 s26, s31, 1
	s_cmp_lg_u32 s31, 2
	s_cselect_b32 s31, s26, 0
	s_add_i32 s26, s28, 1
	s_cmp_lg_u32 s28, 2
	s_cselect_b32 s28, s26, 0
	s_add_i32 s26, s33, 1
	s_cmp_lg_u32 s33, 2
	s_cselect_b32 s33, s26, 0
	s_add_i32 s26, s23, 1
	s_lshl_b32 s101, s31, 14
	s_nop 1
	v_add_u32_e32 v82, s101, v239
	v_add_u32_e32 v102, s101, v240
	ds_read_b128 v[98:101], v82
	ds_read_b128 v[114:117], v82 offset:8192
	ds_read_b128 v[118:121], v102
	s_barrier
	s_cmp_lg_u32 s23, 2
	s_cselect_b32 s23, s26, 0
	s_cmp_lt_u32 s22, s19
	s_mov_b64 s[26:27], -1
	s_cbranch_scc1 .LBB0_317
	s_add_i32 s26, s22, 3
	s_cmp_gt_u32 s26, s17
	s_cbranch_scc1 .LBB0_314
	s_lshl_b32 s26, s28, 14
	s_add_i32 s26, s10, s26
	s_add_i32 s27, s26, 0x2000
	s_mov_b32 m0, s26
	s_add_u32 s100, s8, s50
	s_addc_u32 s101, s9, s51
	global_load_lds_dwordx4 v214, s[100:101]
	s_mov_b32 m0, s27
	s_add_u32 s100, s8, s4
	s_addc_u32 s101, s9, s5
	global_load_lds_dwordx4 v214, s[100:101]

.LBB0_328:
	s_and_b64 vcc, exec, s[26:27]
	s_cbranch_vccz .LBB0_342
	s_lshl_b32 s26, s31, 14
	s_add_i32 s26, s26, 0
	s_nop 1
	s_waitcnt lgkmcnt(0)
	v_mfma_f32_32x32x16_bf16 v[82:97], v[98:101], v[146:149], v[66:81]
	ds_read_b128 v[122:125], v102 offset:8192
	v_mfma_f32_32x32x16_bf16 v[98:113], v[114:117], v[146:149], v[66:81]
	v_add_u32_e32 v126, s26, v241
	ds_read_b128 v[114:117], v126
	v_mfma_f32_32x32x16_bf16 v[82:97], v[118:121], v[150:153], v[82:97]
	ds_read_b128 v[118:121], v126 offset:8192
	s_waitcnt lgkmcnt(0)
	v_mfma_f32_32x32x16_bf16 v[98:113], v[122:125], v[150:153], v[98:113]
	v_add_u32_e32 v126, s26, v242
	ds_read_b128 v[122:125], v126
	v_mfma_f32_32x32x16_bf16 v[82:97], v[114:117], v[154:157], v[82:97]
	ds_read_b128 v[114:117], v126 offset:8192
	v_mfma_f32_32x32x16_bf16 v[98:113], v[118:121], v[154:157], v[98:113]
	s_waitcnt lgkmcnt(0)
	v_mfma_f32_32x32x16_bf16 v[82:97], v[122:125], v[158:161], v[82:97]
	v_mfma_f32_32x32x16_bf16 v[98:113], v[114:117], v[158:161], v[98:113]
	ds_read_b128 v[126:129], v212 offset:49152
	ds_read_b128 v[122:125], v212 offset:53248
	ds_read_b128 v[118:121], v212 offset:57344
	ds_read_b128 v[114:117], v212 offset:61440
	s_add_i32 s26, s20, 64
	s_cmp_le_u32 s26, s16
	s_cbranch_scc1 .LBB0_331
	v_add_u32_e32 v130, s20, v249
	v_add_u32_e32 v130, 0x6f, v130
	v_and_b32_e32 v130, 0x3ffffffc, v130
	v_lshl_add_u32 v162, v130, 2, v244
	ds_read_b128 v[130:133], v162
	ds_read_b128 v[134:137], v162 offset:16
	ds_read_b128 v[138:141], v162 offset:64
	ds_read_b128 v[142:145], v162 offset:80
	s_waitcnt lgkmcnt(0)
	v_pk_add_f32 v[84:85], v[84:85], v[132:133]
	v_pk_add_f32 v[86:87], v[86:87], v[134:135]
	v_pk_add_f32 v[90:91], v[90:91], v[138:139]
	v_pk_add_f32 v[94:95], v[94:95], v[142:143]
	v_pk_add_f32 v[96:97], v[96:97], v[144:145]
	v_pk_add_f32 v[92:93], v[92:93], v[140:141]
	v_pk_add_f32 v[88:89], v[88:89], v[136:137]
	v_pk_add_f32 v[82:83], v[82:83], v[130:131]
	ds_read_b128 v[130:133], v162 offset:128
	ds_read_b128 v[134:137], v162 offset:144
	ds_read_b128 v[138:141], v162 offset:192
	ds_read_b128 v[142:145], v162 offset:208
	s_waitcnt lgkmcnt(0)
	v_pk_add_f32 v[100:101], v[100:101], v[132:133]
	v_pk_add_f32 v[102:103], v[102:103], v[134:135]
	v_pk_add_f32 v[106:107], v[106:107], v[138:139]
	v_pk_add_f32 v[110:111], v[110:111], v[142:143]
	v_pk_add_f32 v[112:113], v[112:113], v[144:145]
	v_pk_add_f32 v[108:109], v[108:109], v[140:141]
	v_pk_add_f32 v[104:105], v[104:105], v[136:137]
	v_pk_add_f32 v[98:99], v[98:99], v[130:131]
